# grid-barrier set-up: the 16 serialized per-XCC census loads of the first barrier issued together and waited once (on v52)
# speedup vs baseline: 1.0188x; 1.0042x over previous
.LBB0_712:
	v_readlane_b32 s8, v253, 17
	v_readlane_b32 s9, v253, 18
	s_nop 4
	global_load_dword v0, v161, s[8:9] sc1
	v_readlane_b32 s8, v253, 19
	v_readlane_b32 s9, v253, 20
	s_nop 4
	global_load_dword v1, v161, s[8:9] sc1
	v_readlane_b32 s8, v253, 21
	v_readlane_b32 s9, v253, 22
	s_nop 4
	global_load_dword v2, v161, s[8:9] sc1
	v_readlane_b32 s8, v253, 23
	v_readlane_b32 s9, v253, 24
	s_nop 4
	global_load_dword v3, v161, s[8:9] sc1
	v_readlane_b32 s8, v253, 25
	v_readlane_b32 s9, v253, 26
	s_nop 4
	global_load_dword v4, v161, s[8:9] sc1
	v_readlane_b32 s8, v253, 27
	v_readlane_b32 s9, v253, 28
	s_nop 4
	global_load_dword v5, v161, s[8:9] sc1
	v_readlane_b32 s8, v253, 29
	v_readlane_b32 s9, v253, 30
	s_nop 4
	global_load_dword v6, v161, s[8:9] sc1
	v_readlane_b32 s8, v253, 31
	v_readlane_b32 s9, v253, 32
	s_nop 4
	global_load_dword v7, v161, s[8:9] sc1
	v_readlane_b32 s8, v253, 33
	v_readlane_b32 s9, v253, 34
	s_nop 4
	global_load_dword v8, v161, s[8:9] sc1
	v_readlane_b32 s8, v253, 35
	v_readlane_b32 s9, v253, 36
	s_nop 4
	global_load_dword v9, v161, s[8:9] sc1
	v_readlane_b32 s8, v253, 37
	v_readlane_b32 s9, v253, 38
	s_nop 4
	global_load_dword v10, v161, s[8:9] sc1
	v_readlane_b32 s8, v253, 39
	v_readlane_b32 s9, v253, 40
	s_nop 4
	global_load_dword v11, v161, s[8:9] sc1
	v_readlane_b32 s8, v253, 41
	v_readlane_b32 s9, v253, 42
	s_nop 4
	global_load_dword v12, v161, s[8:9] sc1
	v_readlane_b32 s8, v253, 43
	v_readlane_b32 s9, v253, 44
	s_nop 4
	global_load_dword v13, v161, s[8:9] sc1
	v_readlane_b32 s8, v253, 45
	v_readlane_b32 s9, v253, 46
	s_nop 4
	global_load_dword v14, v161, s[8:9] sc1
	v_readlane_b32 s8, v253, 47
	v_readlane_b32 s9, v253, 48
	s_nop 4
	global_load_dword v15, v161, s[8:9] sc1
	s_mov_b64 s[10:11], -1
	s_mov_b64 s[8:9], -1
	s_waitcnt vmcnt(0)
	v_add_u32_e32 v16, v1, v0
	v_add_u32_e32 v16, v16, v2
	v_add_u32_e32 v16, v16, v3
	v_add_u32_e32 v16, v16, v4
	v_add_u32_e32 v16, v16, v5
	v_add_u32_e32 v16, v16, v6
	v_add_u32_e32 v16, v16, v7
	v_add_u32_e32 v16, v16, v8
	v_add_u32_e32 v16, v16, v9
	v_add_u32_e32 v16, v16, v10
	v_add_u32_e32 v16, v16, v11
	v_add_u32_e32 v16, v16, v12
	v_add_u32_e32 v16, v16, v13
	v_add_u32_e32 v16, v16, v14
	v_add_u32_e32 v16, v16, v15
	v_cmp_eq_u32_e32 vcc, s14, v16
	s_cbranch_vccnz .LBB0_711
	s_and_b32 s8, s15, 0xff
	s_cmp_eq_u32 s8, 0
	s_mov_b64 s[8:9], -1
	s_mov_b64 s[12:13], -1
	s_sleep 1
	s_cbranch_scc1 .LBB0_716
	s_and_b64 vcc, exec, s[12:13]
	s_cbranch_vccz .LBB0_711
